# rwkv output pass: the six zero-padded neighbour-row reads were 24 predicated 4-byte loads each wrapped in exec save/branch/restore; now six unconditional 16-byte loads masked with v_cndmask
# speedup vs baseline: 1.0045x; 1.0045x over previous
; DI void rwkv_out_phase(const Params& p, int l) {
;     ...
;   for (int t = gw; t < T; t += nw) {
;     const int s = t & (S - 1);
;     const bool hp = s > 0, hn = s < S - 1;
;     const u16* zc = Z + (size_t)t * 1536 + c0;
;     const uint4 z0 = make_uint4(0, 0, 0, 0);
;     const uint4 qr = *(const uint4*)zc, qk = *(const uint4*)(zc + 512), qv = *(const uint4*)(zc + 1024);
;     const uint4 pr = hp ? *(const uint4*)(zc - 1536) : z0, pk = hp ? *(const uint4*)(zc + 512 - 1536) : z0, pv = hp ? *(const uint4*)(zc + 1024 - 1536) : z0;
;     const uint4 nr = hn ? *(const uint4*)(zc + 1536) : z0, nk = hn ? *(const uint4*)(zc + 512 + 1536) : z0, nv = hn ? *(const uint4*)(zc + 1024 + 1536) : z0;
;     const size_t o = (size_t)t * 512 + c0;
;     const uint4 qaf = *(const uint4*)(AF + o), qab = *(const uint4*)(AB + o), qg = *(const uint4*)(GG + o);
;     const uint4 qyf = *(const uint4*)(YF + o), qyb = *(const uint4*)(YB + o);
;     float r[8], k[8], v[8], tp[8], tn[8], ma[8], mb[8];
;     unpack8(qr, r); unpack8(pr, tp); unpack8(nr, tn); load8f(mu0 + c0, ma); load8f(mu1 + c0, mb);
; #pragma unroll
;     for (int j = 0; j < 8; ++j) r[j] = r[j] + ma[j] * (tp[j] - r[j]) + mb[j] * (tn[j] - r[j]);
;     unpack8(qk, k); unpack8(pk, tp); unpack8(nk, tn); load8f(mu0 + 512 + c0, ma); load8f(mu1 + 512 + c0, mb);
; #pragma unroll
;     for (int j = 0; j < 8; ++j) k[j] = k[j] + ma[j] * (tp[j] - k[j]) + mb[j] * (tn[j] - k[j]);
;     unpack8(qv, v); unpack8(pv, tp); unpack8(nv, tn); load8f(mu0 + 1024 + c0, ma); load8f(mu1 + 1024 + c0, mb);
; #pragma unroll
;     for (int j = 0; j < 8; ++j) v[j] = v[j] + ma[j] * (tp[j] - v[j]) + mb[j] * (tn[j] - v[j]);
;     float af[8], ab[8], y[8], yb[8], ka[8], rk[8];
;     unpack8(qaf, af); unpack8(qab, ab); unpack8(qyf, y); unpack8(qyb, yb);
.LBB0_464:
	s_waitcnt vmcnt(1)
	v_cndmask_b32_e64 v18, 0, v180, s[98:99]
	v_cndmask_b32_e64 v1, 0, v181, s[98:99]
	v_cndmask_b32_e64 v20, 0, v182, s[98:99]
	v_cndmask_b32_e64 v19, 0, v183, s[98:99]
	v_cndmask_b32_e64 v23, 0, v184, s[98:99]
	v_cndmask_b32_e64 v21, 0, v185, s[98:99]
	v_cndmask_b32_e64 v51, 0, v186, s[98:99]
	v_cndmask_b32_e64 v50, 0, v187, s[98:99]
	v_cndmask_b32_e64 v53, 0, v188, s[98:99]
	v_cndmask_b32_e64 v54, 0, v189, s[98:99]
	v_cndmask_b32_e64 v58, 0, v190, s[98:99]
	v_cndmask_b32_e64 v55, 0, v191, s[98:99]
	v_cndmask_b32_e64 v56, 0, v192, s[100:101]
	v_cndmask_b32_e64 v52, 0, v193, s[100:101]
	v_cndmask_b32_e64 v59, 0, v194, s[100:101]
	v_cndmask_b32_e64 v57, 0, v195, s[100:101]
	v_cndmask_b32_e64 v61, 0, v196, s[100:101]
	v_cndmask_b32_e64 v60, 0, v197, s[100:101]
	v_cndmask_b32_e64 v63, 0, v198, s[100:101]
	v_cndmask_b32_e64 v62, 0, v199, s[100:101]
	v_lshl_add_u64 v[66:67], v[46:47], 0, v[42:43]
	v_add_co_u32_e32 v10, vcc, 0x20ac8000, v66
	s_mov_b32 s0, 0x24ac8000
	s_nop 0
	v_addc_co_u32_e32 v11, vcc, 0, v67, vcc
	global_load_dwordx4 v[74:77], v[10:11], off
	v_add_co_u32_e32 v10, vcc, s0, v66
	s_mov_b32 s0, 0x28ac8000
	s_nop 0
	v_addc_co_u32_e32 v11, vcc, 0, v67, vcc
	global_load_dwordx4 v[142:145], v[10:11], off
	v_add_co_u32_e32 v10, vcc, s0, v66
	s_mov_b32 s0, 0x62c8000
	s_nop 0
	v_addc_co_u32_e32 v11, vcc, 0, v67, vcc
	v_add_co_u32_e32 v68, vcc, s0, v66
	s_mov_b32 s0, 0xa2c8000
	s_nop 0
	v_addc_co_u32_e32 v69, vcc, 0, v67, vcc
	v_add_co_u32_e32 v66, vcc, s0, v66
	global_load_dwordx4 v[10:13], v[10:11], off
	s_nop 0
	v_addc_co_u32_e32 v67, vcc, 0, v67, vcc
	global_load_dwordx4 v[146:149], v[68:69], off
	global_load_dwordx4 v[150:153], v[66:67], off
	s_waitcnt vmcnt(5)
	v_cndmask_b32_e64 v64, 0, v200, s[100:101]
	v_cndmask_b32_e64 v65, 0, v201, s[100:101]
	v_cndmask_b32_e64 v71, 0, v202, s[100:101]
	v_cndmask_b32_e64 v70, 0, v203, s[100:101]
	v_lshlrev_b32_e32 v136, 16, v14
	v_and_b32_e32 v137, 0xffff0000, v14
	v_lshlrev_b32_e32 v92, 16, v15
	v_and_b32_e32 v93, 0xffff0000, v15
	v_lshlrev_b32_e32 v84, 16, v16
	v_and_b32_e32 v85, 0xffff0000, v16
	v_lshlrev_b32_e32 v14, 16, v17
	v_and_b32_e32 v15, 0xffff0000, v17
	s_waitcnt vmcnt(5)
	v_lshlrev_b32_e32 v138, 16, v18
	v_and_b32_e32 v139, 0xffff0000, v18
	v_lshlrev_b32_e32 v16, 16, v19
	v_and_b32_e32 v17, 0xffff0000, v19
	v_lshlrev_b32_e32 v140, 16, v56
	v_and_b32_e32 v141, 0xffff0000, v56
	v_lshlrev_b32_e32 v94, 16, v59
	v_and_b32_e32 v95, 0xffff0000, v59
	v_lshlrev_b32_e32 v88, 16, v57
	v_and_b32_e32 v89, 0xffff0000, v57
	v_lshlrev_b32_e32 v130, 16, v6
	v_and_b32_e32 v131, 0xffff0000, v6
	v_lshlrev_b32_e32 v106, 16, v7
	v_and_b32_e32 v107, 0xffff0000, v7
	v_lshlrev_b32_e32 v96, 16, v8
	v_and_b32_e32 v97, 0xffff0000, v8
	v_lshlrev_b32_e32 v6, 16, v9
	v_and_b32_e32 v7, 0xffff0000, v9
	v_lshlrev_b32_e32 v102, 16, v51
	v_and_b32_e32 v103, 0xffff0000, v51
	v_lshlrev_b32_e32 v8, 16, v50
	v_and_b32_e32 v9, 0xffff0000, v50
	v_lshlrev_b32_e32 v134, 16, v61
	v_and_b32_e32 v135, 0xffff0000, v61
	v_lshlrev_b32_e32 v112, 16, v60
	v_and_b32_e32 v113, 0xffff0000, v60
	v_lshlrev_b32_e32 v50, 16, v2
	v_and_b32_e32 v51, 0xffff0000, v2
	v_lshlrev_b32_e32 v56, 16, v3
	v_and_b32_e32 v57, 0xffff0000, v3
	v_lshlrev_b32_e32 v66, 16, v4
	v_and_b32_e32 v67, 0xffff0000, v4
	v_lshlrev_b32_e32 v18, 16, v5
	v_and_b32_e32 v19, 0xffff0000, v5
	v_lshlrev_b32_e32 v68, 16, v58
	v_and_b32_e32 v69, 0xffff0000, v58
	v_lshlrev_b32_e32 v72, 16, v71
	v_and_b32_e32 v73, 0xffff0000, v71
	v_lshlrev_b32_e32 v80, 16, v70
	v_and_b32_e32 v81, 0xffff0000, v70
	v_pk_add_f32 v[138:139], v[138:139], v[136:137] neg_lo:[0,1] neg_hi:[0,1]
	v_lshlrev_b32_e32 v132, 16, v23
	v_and_b32_e32 v133, 0xffff0000, v23
	v_pk_add_f32 v[132:133], v[132:133], v[130:131] neg_lo:[0,1] neg_hi:[0,1]
	v_lshlrev_b32_e32 v100, 16, v1
	v_and_b32_e32 v101, 0xffff0000, v1
	v_lshlrev_b32_e32 v104, 16, v52
	v_and_b32_e32 v105, 0xffff0000, v52
	s_waitcnt vmcnt(4)
	v_lshlrev_b32_e32 v126, 16, v74
	v_and_b32_e32 v127, 0xffff0000, v74
	v_lshlrev_b32_e32 v122, 16, v75
	v_and_b32_e32 v123, 0xffff0000, v75
	v_lshlrev_b32_e32 v118, 16, v76
	v_and_b32_e32 v119, 0xffff0000, v76
	v_lshlrev_b32_e32 v114, 16, v77
	v_and_b32_e32 v115, 0xffff0000, v77
	s_waitcnt vmcnt(3)
	v_lshlrev_b32_e32 v128, 16, v142
	v_and_b32_e32 v129, 0xffff0000, v142
	v_lshlrev_b32_e32 v124, 16, v143
	v_and_b32_e32 v125, 0xffff0000, v143
	v_lshlrev_b32_e32 v120, 16, v144
	v_and_b32_e32 v121, 0xffff0000, v144
	v_lshlrev_b32_e32 v116, 16, v145
	v_and_b32_e32 v117, 0xffff0000, v145
	v_pk_add_f32 v[100:101], v[100:101], v[92:93] neg_lo:[0,1] neg_hi:[0,1]
	v_lshlrev_b32_e32 v90, 16, v20
	v_and_b32_e32 v91, 0xffff0000, v20
	v_lshlrev_b32_e32 v110, 16, v21
	v_and_b32_e32 v111, 0xffff0000, v21
	v_pk_add_f32 v[126:127], v[126:127], v[128:129]
	s_waitcnt vmcnt(1)
	v_lshlrev_b32_e32 v58, 16, v146
	v_and_b32_e32 v59, 0xffff0000, v146
	v_lshlrev_b32_e32 v70, 16, v147
	v_and_b32_e32 v71, 0xffff0000, v147
	v_lshlrev_b32_e32 v76, 16, v148
	v_and_b32_e32 v77, 0xffff0000, v148
	v_lshlrev_b32_e32 v82, 16, v149
	v_and_b32_e32 v83, 0xffff0000, v149
	s_waitcnt vmcnt(0)
; DI float red8(float x) { x += dpp_f<0xB1>(x); x += dpp_f<0x4E>(x); x += dpp_f<0x141>(x); return x; }
; DI void rwkv_out_phase(const Params& p, int l) {
;     ...
;     unpack8(qr, r); unpack8(pr, tp); unpack8(nr, tn); load8f(mu0 + c0, ma); load8f(mu1 + c0, mb);
; #pragma unroll
;     for (int j = 0; j < 8; ++j) r[j] = r[j] + ma[j] * (tp[j] - r[j]) + mb[j] * (tn[j] - r[j]);
;     unpack8(qk, k); unpack8(pk, tp); unpack8(nk, tn); load8f(mu0 + 512 + c0, ma); load8f(mu1 + 512 + c0, mb);
; #pragma unroll
;     for (int j = 0; j < 8; ++j) k[j] = k[j] + ma[j] * (tp[j] - k[j]) + mb[j] * (tn[j] - k[j]);
;     unpack8(qv, v); unpack8(pv, tp); unpack8(nv, tn); load8f(mu0 + 1024 + c0, ma); load8f(mu1 + 1024 + c0, mb);
; #pragma unroll
;     for (int j = 0; j < 8; ++j) v[j] = v[j] + ma[j] * (tp[j] - v[j]) + mb[j] * (tn[j] - v[j]);
;     float af[8], ab[8], y[8], yb[8], ka[8], rk[8];
;     unpack8(qaf, af); unpack8(qab, ab); unpack8(qyf, y); unpack8(qyb, yb);
;     load8f(p.k_a + l * 512 + c0, ka); load8f(p.r_k + l * 512 + c0, rk);
;     float sy = 0.f, sb = 0.f;
; #pragma unroll
;     for (int j = 0; j < 8; ++j) {
;       y[j] += yb[j]; sy += y[j];
;       const float kb = k[j] * (1.f + (0.5f * (af[j] + ab[j]) - 1.f) * ka[j]);
;       sb += r[j] * kb * rk[j];
;     }
;     const float mean = red8(sy) * (1.f / 64.f);
	v_lshlrev_b32_e32 v60, 16, v150
	v_and_b32_e32 v61, 0xffff0000, v150
	v_lshlrev_b32_e32 v74, 16, v151
	v_and_b32_e32 v75, 0xffff0000, v151
	v_lshlrev_b32_e32 v78, 16, v152
	v_and_b32_e32 v79, 0xffff0000, v152
	v_lshlrev_b32_e32 v86, 16, v153
	v_and_b32_e32 v87, 0xffff0000, v153
	global_load_dwordx4 v[2:5], v[24:25], off offset:16
	global_load_dwordx4 v[142:145], v[24:25], off
	global_load_dwordx4 v[146:149], v[26:27], off offset:16
	global_load_dwordx4 v[150:153], v[26:27], off
	v_pk_add_f32 v[90:91], v[90:91], v[84:85] neg_lo:[0,1] neg_hi:[0,1]
	v_pk_fma_f32 v[126:127], v[126:127], 0.5, -1.0 op_sel_hi:[1,0,0]
	v_lshlrev_b32_e32 v108, 16, v63
	v_and_b32_e32 v109, 0xffff0000, v63
	v_lshlrev_b32_e32 v98, 16, v62
	v_and_b32_e32 v99, 0xffff0000, v62
	v_lshlrev_b32_e32 v20, 16, v55
	v_and_b32_e32 v21, 0xffff0000, v55
	v_pk_add_f32 v[20:21], v[20:21], v[18:19] neg_lo:[0,1] neg_hi:[0,1]
	v_lshlrev_b32_e32 v52, 16, v53
	v_and_b32_e32 v53, 0xffff0000, v53
	v_lshlrev_b32_e32 v62, 16, v54
	v_and_b32_e32 v63, 0xffff0000, v54
	v_lshlrev_b32_e32 v54, 16, v64
	v_and_b32_e32 v55, 0xffff0000, v64
	v_pk_add_f32 v[52:53], v[52:53], v[50:51] neg_lo:[0,1] neg_hi:[0,1]
	v_lshlrev_b32_e32 v64, 16, v65
	v_and_b32_e32 v65, 0xffff0000, v65
	v_pk_add_f32 v[62:63], v[62:63], v[56:57] neg_lo:[0,1] neg_hi:[0,1]
	v_pk_add_f32 v[68:69], v[68:69], v[66:67] neg_lo:[0,1] neg_hi:[0,1]
	v_add_u32_e32 v22, s33, v22
	v_readlane_b32 s0, v237, 25
	v_readlane_b32 s1, v237, 26
	v_lshl_add_u64 v[46:47], v[46:47], 0, s[38:39]
	s_waitcnt vmcnt(3)
	v_pk_fma_f32 v[2:3], v[90:91], v[2:3], v[84:85]
	s_waitcnt vmcnt(2)
	v_pk_fma_f32 v[138:139], v[138:139], v[142:143], v[136:137]
	v_pk_add_f32 v[136:137], v[140:141], v[136:137] neg_lo:[0,1] neg_hi:[0,1]
	v_pk_fma_f32 v[100:101], v[100:101], v[144:145], v[92:93]
	s_waitcnt vmcnt(0)
	v_pk_fma_f32 v[150:151], v[136:137], v[150:151], v[138:139]
	global_load_dwordx4 v[136:139], v[24:25], off offset:2064
	global_load_dwordx4 v[140:143], v[24:25], off offset:2048
	global_load_dwordx4 v[154:157], v[28:29], off offset:16
	global_load_dwordx4 v[158:161], v[28:29], off
	v_pk_add_f32 v[92:93], v[104:105], v[92:93] neg_lo:[0,1] neg_hi:[0,1]
	v_pk_add_f32 v[104:105], v[112:113], v[106:107] neg_lo:[0,1] neg_hi:[0,1]
	v_pk_fma_f32 v[92:93], v[92:93], v[152:153], v[100:101]
	v_pk_add_f32 v[100:101], v[110:111], v[106:107] neg_lo:[0,1] neg_hi:[0,1]
	v_pk_add_f32 v[84:85], v[94:95], v[84:85] neg_lo:[0,1] neg_hi:[0,1]
	v_pk_add_f32 v[90:91], v[108:109], v[96:97] neg_lo:[0,1] neg_hi:[0,1]
	v_pk_fma_f32 v[2:3], v[84:85], v[146:147], v[2:3]
	v_pk_add_f32 v[84:85], v[102:103], v[96:97] neg_lo:[0,1] neg_hi:[0,1]
	v_lshlrev_b32_e32 v94, 16, v10
	v_and_b32_e32 v95, 0xffff0000, v10
	v_lshl_add_u64 v[48:49], v[48:49], 0, s[0:1]
	s_waitcnt vmcnt(3)
	v_pk_fma_f32 v[84:85], v[84:85], v[136:137], v[96:97]
	s_waitcnt vmcnt(2)
	v_pk_fma_f32 v[132:133], v[132:133], v[140:141], v[130:131]
	v_pk_add_f32 v[130:131], v[134:135], v[130:131] neg_lo:[0,1] neg_hi:[0,1]
	v_pk_fma_f32 v[100:101], v[100:101], v[142:143], v[106:107]
	s_waitcnt vmcnt(0)
	v_pk_fma_f32 v[134:135], v[130:131], v[158:159], v[132:133]
	global_load_dwordx4 v[130:133], v[34:35], off offset:16
	global_load_dwordx4 v[162:165], v[34:35], off
	global_load_dwordx4 v[170:173], v[36:37], off offset:16
	global_load_dwordx4 v[174:177], v[36:37], off
	v_pk_fma_f32 v[100:101], v[104:105], v[160:161], v[100:101]
	v_pk_add_f32 v[104:105], v[122:123], v[124:125]
	v_pk_fma_f32 v[84:85], v[90:91], v[154:155], v[84:85]
	v_pk_fma_f32 v[104:105], v[104:105], 0.5, -1.0 op_sel_hi:[1,0,0]
	v_pk_add_f32 v[90:91], v[118:119], v[120:121]
	s_waitcnt vmcnt(2)
	v_pk_fma_f32 v[126:127], v[126:127], v[162:163], 1.0 op_sel_hi:[1,1,0]
	s_nop 0
	v_pk_mul_f32 v[126:127], v[134:135], v[126:127]
	v_pk_fma_f32 v[104:105], v[104:105], v[164:165], 1.0 op_sel_hi:[1,1,0]
	v_pk_mul_f32 v[126:127], v[150:151], v[126:127]
	v_pk_mul_f32 v[100:101], v[100:101], v[104:105]
	s_waitcnt vmcnt(0)
	v_pk_mul_f32 v[126:127], v[126:127], v[174:175]
	v_pk_fma_f32 v[90:91], v[90:91], 0.5, -1.0 op_sel_hi:[1,0,0]
	v_add_f32_e32 v1, 0, v126
	v_pk_mul_f32 v[92:93], v[92:93], v[100:101]
	v_pk_fma_f32 v[90:91], v[90:91], v[130:131], 1.0 op_sel_hi:[1,1,0]
	v_add_f32_e32 v1, v1, v127
	v_pk_mul_f32 v[92:93], v[92:93], v[176:177]
	v_pk_mul_f32 v[84:85], v[84:85], v[90:91]
	v_add_f32_e32 v1, v1, v92
	v_pk_mul_f32 v[2:3], v[2:3], v[84:85]
	v_add_f32_e32 v1, v1, v93
	v_pk_mul_f32 v[2:3], v[2:3], v[170:171]
	v_lshlrev_b32_e32 v92, 16, v11
	v_add_f32_e32 v1, v1, v2
	v_add_f32_e32 v1, v1, v3
	v_pk_add_f32 v[2:3], v[16:17], v[14:15] neg_lo:[0,1] neg_hi:[0,1]
	v_and_b32_e32 v93, 0xffff0000, v11
	v_pk_fma_f32 v[2:3], v[2:3], v[4:5], v[14:15]
	v_pk_add_f32 v[4:5], v[88:89], v[14:15] neg_lo:[0,1] neg_hi:[0,1]
	v_lshlrev_b32_e32 v90, 16, v12
	v_pk_fma_f32 v[2:3], v[4:5], v[148:149], v[2:3]
	v_pk_add_f32 v[4:5], v[8:9], v[6:7] neg_lo:[0,1] neg_hi:[0,1]
	v_and_b32_e32 v91, 0xffff0000, v12
	v_pk_fma_f32 v[4:5], v[4:5], v[138:139], v[6:7]
	v_pk_add_f32 v[6:7], v[98:99], v[6:7] neg_lo:[0,1] neg_hi:[0,1]
	v_lshlrev_b32_e32 v88, 16, v13
	v_pk_fma_f32 v[4:5], v[6:7], v[156:157], v[4:5]
	v_pk_add_f32 v[6:7], v[114:115], v[116:117]
	v_and_b32_e32 v89, 0xffff0000, v13
	v_pk_fma_f32 v[6:7], v[6:7], 0.5, -1.0 op_sel_hi:[1,0,0]
	s_nop 0
	v_pk_fma_f32 v[6:7], v[6:7], v[132:133], 1.0 op_sel_hi:[1,1,0]
	s_nop 0
	v_pk_mul_f32 v[4:5], v[4:5], v[6:7]
	s_nop 0
	v_pk_mul_f32 v[2:3], v[2:3], v[4:5]
	s_nop 0
	v_pk_mul_f32 v[2:3], v[2:3], v[172:173]
	s_nop 0
	v_add_f32_e32 v1, v1, v2
	v_add_f32_e32 v1, v1, v3
	global_load_dwordx4 v[6:9], v[30:31], off offset:16
	global_load_dwordx4 v[2:5], v[30:31], off
	global_load_dwordx4 v[10:13], v[32:33], off offset:16
	global_load_dwordx4 v[14:17], v[32:33], off
	v_add_f32_dpp v1, v1, v1 quad_perm:[1,0,3,2] row_mask:0xf bank_mask:0xf bound_ctrl:1
	s_waitcnt vmcnt(3)
; DI unsigned pack2(float a, float b) { f32x2_t v = {a, b}; bf16x2_t r = __builtin_convertvector(v, bf16x2_t); return __builtin_bit_cast(unsigned, r); }
; DI float red8(float x) { x += dpp_f<0xB1>(x); x += dpp_f<0x4E>(x); x += dpp_f<0x141>(x); return x; }
; DI void rwkv_out_phase(const Params& p, int l) {
;     ...
;     const int s = t & (S - 1);
;     const bool hp = s > 0, hn = s < S - 1;
;     const u16* zc = Z + (size_t)t * 1536 + c0;
;     const uint4 z0 = make_uint4(0, 0, 0, 0);
;     const uint4 qr = *(const uint4*)zc, qk = *(const uint4*)(zc + 512), qv = *(const uint4*)(zc + 1024);
;     const uint4 pr = hp ? *(const uint4*)(zc - 1536) : z0, pk = hp ? *(const uint4*)(zc + 512 - 1536) : z0, pv = hp ? *(const uint4*)(zc + 1024 - 1536) : z0;
;     const uint4 nr = hn ? *(const uint4*)(zc + 1536) : z0, nk = hn ? *(const uint4*)(zc + 512 + 1536) : z0, nv = hn ? *(const uint4*)(zc + 1024 + 1536) : z0;
;     ...
;     const float mean = red8(sy) * (1.f / 64.f);
;     const float bs = red8(sb);
;     float sv = 0.f;
; #pragma unroll
;     for (int j = 0; j < 8; ++j) { y[j] -= mean; sv += y[j] * y[j]; }
;     const float rstd = rsqrtf(red8(sv) * (1.f / 64.f) + 64e-5f);
;     float g[8], gg[8], gb[8];
;     unpack8(qg, g); load8f(p.gn_g + l * 512 + c0, gg); load8f(p.gn_b + l * 512 + c0, gb);
;     float ov[8];
; #pragma unroll
;     for (int j = 0; j < 8; ++j) ov[j] = (y[j] * rstd * gg[j] + gb[j] + bs * v[j]) * g[j];
;     uint4 oo; oo.x = pack2(ov[0], ov[1]); oo.y = pack2(ov[2], ov[3]); oo.z = pack2(ov[4], ov[5]); oo.w = pack2(ov[6], ov[7]);
;     *(uint4*)(CC + (size_t)t * 1024 + 512 + c0) = oo;
	v_pk_fma_f32 v[8:9], v[20:21], v[8:9], v[18:19]
	v_pk_add_f32 v[18:19], v[80:81], v[18:19] neg_lo:[0,1] neg_hi:[0,1]
	s_waitcnt vmcnt(2)
	v_pk_fma_f32 v[2:3], v[52:53], v[2:3], v[50:51]
	s_waitcnt vmcnt(1)
	v_pk_fma_f32 v[8:9], v[18:19], v[12:13], v[8:9]
	v_pk_add_f32 v[12:13], v[82:83], v[86:87]
	global_load_dwordx4 v[18:21], v[38:39], off offset:16
	global_load_dwordx4 v[80:83], v[38:39], off
	global_load_dwordx4 v[96:99], v[40:41], off offset:16
	global_load_dwordx4 v[100:103], v[40:41], off
	v_pk_add_f32 v[50:51], v[54:55], v[50:51] neg_lo:[0,1] neg_hi:[0,1]
	v_add_f32_dpp v1, v1, v1 quad_perm:[2,3,0,1] row_mask:0xf bank_mask:0xf bound_ctrl:1
	s_waitcnt vmcnt(4)
	v_pk_fma_f32 v[2:3], v[50:51], v[14:15], v[2:3]
	v_pk_add_f32 v[14:15], v[58:59], v[60:61]
	v_add_f32_dpp v84, v1, v1 row_half_mirror row_mask:0xf bank_mask:0xf bound_ctrl:1
	v_pk_fma_f32 v[4:5], v[62:63], v[4:5], v[56:57]
	v_pk_add_f32 v[56:57], v[64:65], v[56:57] neg_lo:[0,1] neg_hi:[0,1]
	v_add_f32_e32 v1, 0, v14
	v_pk_fma_f32 v[4:5], v[56:57], v[16:17], v[4:5]
	v_pk_add_f32 v[16:17], v[70:71], v[74:75]
	v_add_f32_e32 v1, v15, v1
	v_pk_fma_f32 v[6:7], v[68:69], v[6:7], v[66:67]
	v_pk_add_f32 v[66:67], v[72:73], v[66:67] neg_lo:[0,1] neg_hi:[0,1]
	v_add_f32_e32 v1, v16, v1
	v_pk_fma_f32 v[6:7], v[66:67], v[10:11], v[6:7]
	v_pk_add_f32 v[10:11], v[76:77], v[78:79]
	v_add_f32_e32 v1, v17, v1
	v_add_f32_e32 v1, v10, v1
	v_add_f32_e32 v1, v11, v1
	v_add_f32_e32 v1, v12, v1
	v_add_f32_e32 v1, v13, v1
	s_nop 1
	v_add_f32_dpp v1, v1, v1 quad_perm:[1,0,3,2] row_mask:0xf bank_mask:0xf bound_ctrl:1
	s_nop 1
	v_add_f32_dpp v1, v1, v1 quad_perm:[2,3,0,1] row_mask:0xf bank_mask:0xf bound_ctrl:1
	s_nop 1
	v_add_f32_dpp v1, v1, v1 row_half_mirror row_mask:0xf bank_mask:0xf bound_ctrl:1
	v_mul_f32_e32 v50, 0x3c800000, v1
	v_pk_add_f32 v[14:15], v[14:15], v[50:51] op_sel_hi:[1,0] neg_lo:[0,1] neg_hi:[0,1]
	v_pk_add_f32 v[16:17], v[16:17], v[50:51] op_sel_hi:[1,0] neg_lo:[0,1] neg_hi:[0,1]
	v_pk_mul_f32 v[52:53], v[14:15], v[14:15]
	v_pk_mul_f32 v[54:55], v[16:17], v[16:17]
	v_add_f32_e32 v1, v52, v53
	v_pk_add_f32 v[10:11], v[10:11], v[50:51] op_sel_hi:[1,0] neg_lo:[0,1] neg_hi:[0,1]
	v_add_f32_e32 v1, v54, v1
	v_pk_mul_f32 v[56:57], v[10:11], v[10:11]
	v_add_f32_e32 v1, v55, v1
	v_pk_add_f32 v[12:13], v[12:13], v[50:51] op_sel_hi:[1,0] neg_lo:[0,1] neg_hi:[0,1]
	v_add_f32_e32 v1, v56, v1
	v_pk_mul_f32 v[50:51], v[12:13], v[12:13]
	v_add_f32_e32 v1, v57, v1
	v_add_f32_e32 v1, v50, v1
	v_add_f32_e32 v1, v51, v1
	s_nop 1
	v_add_f32_dpp v1, v1, v1 quad_perm:[1,0,3,2] row_mask:0xf bank_mask:0xf bound_ctrl:1
	s_nop 1
	v_add_f32_dpp v1, v1, v1 quad_perm:[2,3,0,1] row_mask:0xf bank_mask:0xf bound_ctrl:1
	s_nop 1
	v_add_f32_dpp v1, v1, v1 row_half_mirror row_mask:0xf bank_mask:0xf bound_ctrl:1
	v_fmamk_f32 v1, v1, 0x3c800000, v211
	v_cmp_gt_f32_e32 vcc, s51, v1
	v_mul_f32_e32 v23, 0x4b800000, v1
	s_nop 0
	v_cndmask_b32_e32 v1, v1, v23, vcc
	v_rsq_f32_e32 v1, v1
	s_nop 0
	v_mul_f32_e32 v23, 0x45800000, v1
	v_cndmask_b32_e32 v50, v1, v23, vcc
	v_pk_mul_f32 v[14:15], v[14:15], v[50:51] op_sel_hi:[1,0]
	v_pk_mul_f32 v[10:11], v[10:11], v[50:51] op_sel_hi:[1,0]
	s_waitcnt vmcnt(0)
	v_pk_fma_f32 v[14:15], v[80:81], v[14:15], v[100:101]
	s_nop 0
	v_pk_fma_f32 v[2:3], v[2:3], v[84:85], v[14:15] op_sel_hi:[1,0,1]
	v_pk_mul_f32 v[14:15], v[16:17], v[50:51] op_sel_hi:[1,0]
	v_pk_fma_f32 v[10:11], v[18:19], v[10:11], v[96:97]
	v_pk_fma_f32 v[14:15], v[82:83], v[14:15], v[102:103]
	v_pk_fma_f32 v[6:7], v[6:7], v[84:85], v[10:11] op_sel_hi:[1,0,1]
	v_pk_fma_f32 v[4:5], v[4:5], v[84:85], v[14:15] op_sel_hi:[1,0,1]
	v_pk_mul_f32 v[2:3], v[2:3], v[94:95]
	v_pk_mul_f32 v[4:5], v[4:5], v[92:93]
	v_pk_mul_f32 v[6:7], v[6:7], v[90:91]
	v_pk_mul_f32 v[10:11], v[12:13], v[50:51] op_sel_hi:[1,0]
	v_cvt_pk_bf16_f32 v2, v2, v3
	v_cvt_pk_bf16_f32 v3, v4, v5
	v_cvt_pk_bf16_f32 v4, v6, v7
	v_lshl_add_u64 v[6:7], v[44:45], 0, v[42:43]
	v_pk_fma_f32 v[10:11], v[20:21], v[10:11], v[98:99]
	v_add_co_u32_e32 v6, vcc, 0x2cac8000, v6
	v_pk_fma_f32 v[8:9], v[8:9], v[84:85], v[10:11] op_sel_hi:[1,0,1]
	s_nop 0
	v_addc_co_u32_e32 v7, vcc, 0, v7, vcc
	v_pk_mul_f32 v[8:9], v[8:9], v[88:89]
	v_cmp_lt_u32_e32 vcc, s63, v22
	v_cvt_pk_bf16_f32 v5, v8, v9
	v_lshl_add_u64 v[44:45], v[44:45], 0, s[36:37]
	s_or_b64 s[22:23], vcc, s[22:23]
	global_store_dwordx4 v[6:7], v[2:5], off offset:1024
	s_andn2_b64 exec, exec, s[22:23]
	s_cbranch_execz .LBB0_513
.LBB0_465:
	v_lshl_add_u64 v[10:11], v[48:49], 0, v[42:43]
	v_add_co_u32_e32 v2, vcc, 0xe2c8000, v10
	v_and_b32_e32 v12, 0x1fff, v22
	s_nop 0
	v_addc_co_u32_e32 v3, vcc, 0, v11, vcc
	global_load_dwordx4 v[14:17], v[2:3], off
	global_load_dwordx4 v[6:9], v[2:3], off offset:1024
	v_add_co_u32_e32 v204, vcc, 0xe2c7000, v10
	global_load_dwordx4 v[2:5], v[2:3], off offset:2048
	v_addc_co_u32_e32 v205, vcc, 0, v11, vcc
	v_cmp_ne_u32_e64 s[98:99], 0, v12
	v_cmp_ne_u32_e64 s[100:101], s26, v12
	v_readlane_b32 s36, v237, 35
	global_load_dwordx4 v[180:183], v[204:205], off offset:1024
	global_load_dwordx4 v[184:187], v[204:205], off offset:2048
	v_readlane_b32 s38, v237, 37
	global_load_dwordx4 v[188:191], v[204:205], off offset:3072
	v_readlane_b32 s37, v237, 36
	v_add_co_u32_e32 v204, vcc, 0xe2c8000, v10
	v_readlane_b32 s39, v237, 38
	v_addc_co_u32_e32 v205, vcc, 0, v11, vcc
	s_nop 0
	global_load_dwordx4 v[192:195], v[204:205], off offset:3072
	v_add_co_u32_e32 v204, vcc, 0xe2c9000, v10
	s_nop 1
	v_addc_co_u32_e32 v205, vcc, 0, v11, vcc
	s_nop 0
	global_load_dwordx4 v[196:199], v[204:205], off
	global_load_dwordx4 v[200:203], v[204:205], off offset:1024
	s_branch .LBB0_464
